# baseline (speedup 1.0000x reference)
; #define LAS __attribute__((address_space(3)))
; #define GAS __attribute__((address_space(1)))
; #define ATT_KRD(KOFF, DLO, DHI) do { _Pragma("unroll") for (int d0 = (DLO); d0 < (DHI); ++d0) { kf[2 * d0] = *(const LAS bf16x8*)(lds + (KOFF) + kr + 2 * d0 * KCH); kf[2 * d0 + 1] = *(const LAS bf16x8*)(lds + (KOFF) + kr + 2 * d0 * KCH + 512); } } while (0)
; __device__ __forceinline__ void attn_unit(LAS unsigned char* lds, bf16_t* Qm, const bf16_t* __restrict__ Kb, const bf16_t* __restrict__ Vt,
;                                           int b, int h, int qb, int lgS, float lam, float oscale, const float* __restrict__ subg, float* stash) {
;     ...
;         const bf16_t* qp = Qm + (size_t)(tok0 + r32) * MIXW + (2 * h + c) * 64 + hi * 8;
;         bf16x8 qf[4];
; #pragma unroll
;         for (int d0 = 0; d0 < 4; ++d0) qf[d0] = *(const GAS bf16x8*)(qp + d0 * 16);
; #pragma unroll
;         for (int i = 0; i < 4; ++i)
; #pragma unroll
;             for (int r = 0; r < 16; ++r) o[i][r] = 0.f;
;         float mhat, lrun;
;         f32x16 negm;
; #pragma unroll
;         for (int r = 0; r < 16; ++r) negm[r] = 0.f;
;         const bf16_t* kg = Kb + (size_t)((b << lgS) + (tid >> 3)) * 512 + (2 * h + c) * 64 + (tid & 7) * 8;
;         const bf16_t* vg0 = Vt + ((size_t)(b * 512 + h * 128 + (tid >> 3)) << lgS) + (tid & 7) * 8;
;         const bf16_t* vg1 = vg0 + ((size_t)64 << lgS);
;         u32x4 kreg, vreg0, vreg1;
;         {
;             kreg = *(const GAS u32x4*)kg; vreg0 = *(const GAS u32x4*)vg0; vreg1 = *(const GAS u32x4*)vg1;
;             const u32x4 k1 = *(const GAS u32x4*)(kg + (size_t)64 * 512), k2 = *(const GAS u32x4*)(kg + (size_t)2 * 64 * 512), v10 = *(const GAS u32x4*)(vg0 + 64), v11 = *(const GAS u32x4*)(vg1 + 64);
;             *(LAS u32x4*)(lds + kw) = kreg; *(LAS u32x4*)(lds + vw0) = vreg0; *(LAS u32x4*)(lds + vw1) = vreg1;
;             *(LAS u32x4*)(lds + KBUF + kw) = k1; *(LAS u32x4*)(lds + VBUF + vw0) = v10; *(LAS u32x4*)(lds + VBUF + vw1) = v11;
;             *(LAS u32x4*)(lds + 2 * KBUF + kw) = k2;
;             kreg = *(const GAS u32x4*)(kg + (size_t)3 * 64 * 512); vreg0 = *(const GAS u32x4*)(vg0 + 2 * 64); vreg1 = *(const GAS u32x4*)(vg1 + 2 * 64);
;         }
;         __syncthreads();
;         u32x4 pk[4]; bf16x8 kf[8]; bf16x8 vfa[4], vfb[4];
;         {
;             f32x16 p0, p1;
;             ATT_KRD(0, 0, 4);
;             ATT_QK(p0, p1);
.LBB0_334:
	s_or_b32 s90, s25, s5
	s_lshl_b64 s[28:29], s[90:91], 1
	v_lshl_add_u64 v[12:13], v[228:229], 0, s[28:29]
	v_add_co_u32_e32 v4, vcc, 0x10000, v12
	v_lshl_add_u64 v[14:15], v[226:227], 0, s[28:29]
	s_nop 0
	v_addc_co_u32_e32 v5, vcc, 0, v13, vcc
	global_load_dwordx4 v[0:3], v[12:13], off
	s_nop 0
	global_load_dwordx4 v[4:7], v[4:5], off
	v_add_co_u32_e32 v8, vcc, 0x20000, v12
	v_add_u32_e32 v16, 0, v234
	s_nop 0
	v_addc_co_u32_e32 v9, vcc, 0, v13, vcc
	global_load_dwordx4 v[8:11], v[8:9], off
	s_nop 0
	global_load_dwordx4 v[136:139], v[14:15], off
	global_load_dwordx4 v[140:143], v[14:15], off offset:32
	global_load_dwordx4 v[144:147], v[14:15], off offset:64
	global_load_dwordx4 v[148:151], v[14:15], off offset:96
	v_add_co_u32_e32 v12, vcc, 0x30000, v12
	s_waitcnt vmcnt(8)
	v_mov_b64_e32 v[170:171], v[130:131]
	v_addc_co_u32_e32 v13, vcc, 0, v13, vcc
	global_load_dwordx4 v[152:155], v[12:13], off
	s_waitcnt vmcnt(8)
	v_mov_b64_e32 v[178:179], v[134:135]
	v_lshl_add_u64 v[238:239], v[236:237], 0, s[28:29]
	s_mov_b32 s56, 0x9000
	s_movk_i32 s50, 0x2100
	s_movk_i32 s29, 0x4200
	s_movk_i32 s25, 0x4800
	s_movk_i32 s90, 0xc0
	v_mov_b64_e32 v[168:169], v[128:129]
	v_mov_b64_e32 v[176:177], v[132:133]
	s_mov_b32 s28, 0
	s_mov_b32 s57, 0
	s_mov_b32 s60, 0
	s_waitcnt vmcnt(7)
	ds_write_b128 v248, v[0:3]
	ds_write_b128 v16, v[112:115] offset:25344
	ds_write_b128 v16, v[116:119] offset:34560
	s_waitcnt vmcnt(6)
	ds_write_b128 v248, v[4:7] offset:8448
	ds_write_b128 v16, v[120:123] offset:43776
	ds_write_b128 v16, v[124:127] offset:52992
	s_waitcnt vmcnt(5)
	ds_write_b128 v248, v[8:11] offset:16896
	s_waitcnt lgkmcnt(0)
	s_barrier
	ds_read_b128 v[0:3], v235
	ds_read_b128 v[18:21], v235 offset:512
	s_waitcnt vmcnt(4) lgkmcnt(1)
	v_mfma_f32_32x32x16_bf16 v[2:17], v[0:3], v[136:139], 0
	ds_read_b128 v[34:37], v235 offset:2112
	ds_read_b128 v[38:41], v235 offset:2624
	v_mov_b32_e32 v0, 0
	v_mov_b32_e32 v51, v0
	v_mov_b32_e32 v52, v0
	v_mov_b32_e32 v53, v0
	v_mov_b32_e32 v54, v0
	v_mov_b32_e32 v55, v0
	s_waitcnt lgkmcnt(2)
	v_mfma_f32_32x32x16_bf16 v[18:33], v[18:21], v[136:139], 0
	v_mov_b32_e32 v56, v0
	v_mov_b32_e32 v57, v0
	v_mov_b32_e32 v58, v0
	v_mov_b32_e32 v59, v0
	v_mov_b32_e32 v60, v0
	v_mov_b32_e32 v61, v0
	v_mov_b32_e32 v62, v0
	s_waitcnt vmcnt(3) lgkmcnt(1)
	v_mfma_f32_32x32x16_bf16 v[2:17], v[34:37], v[140:143], v[2:17]
	v_mov_b32_e32 v63, v0
	s_waitcnt lgkmcnt(0)
	v_mfma_f32_32x32x16_bf16 v[18:33], v[38:41], v[140:143], v[18:33]
	ds_read_b128 v[34:37], v235 offset:4224
	ds_read_b128 v[38:41], v235 offset:4736
	s_waitcnt vmcnt(2) lgkmcnt(1)
	v_mfma_f32_32x32x16_bf16 v[2:17], v[34:37], v[144:147], v[2:17]
	ds_read_b128 v[34:37], v235 offset:6336
	s_waitcnt lgkmcnt(1)
	v_mfma_f32_32x32x16_bf16 v[18:33], v[38:41], v[144:147], v[18:33]
	ds_read_b128 v[38:41], v235 offset:6848
	ds_read_b128 v[156:159], v235 offset:8448
	ds_read_b128 v[160:163], v235 offset:8960
	ds_read_b128 v[204:207], v235 offset:10560
	ds_read_b128 v[208:211], v235 offset:11072
	ds_read_b128 v[212:215], v235 offset:12672
	ds_read_b128 v[216:219], v235 offset:13184
	ds_read_b128 v[222:225], v235 offset:14784
	ds_read_b128 v[240:243], v235 offset:15296
	ds_read_b128 v[196:199], v220 offset:25344
	ds_read_b128 v[192:195], v220 offset:29952
	ds_read_b128 v[188:191], v220 offset:34560
	ds_read_b128 v[184:187], v220 offset:39168
	s_waitcnt lgkmcnt(0)
	s_barrier
; #define LAS __attribute__((address_space(3)))
; __device__ __forceinline__ unsigned cvtpk_s(float lo, float hi) { f32x2_t v = {lo, hi}; bf16x2_t b = __builtin_convertvector(v, bf16x2_t); return __builtin_bit_cast(unsigned, b); }
; #define ATT_KRD(KOFF, DLO, DHI) do { _Pragma("unroll") for (int d0 = (DLO); d0 < (DHI); ++d0) { kf[2 * d0] = *(const LAS bf16x8*)(lds + (KOFF) + kr + 2 * d0 * KCH); kf[2 * d0 + 1] = *(const LAS bf16x8*)(lds + (KOFF) + kr + 2 * d0 * KCH + 512); } } while (0)
; #define ATT_MX3(a, b, c) __builtin_fmaxf(__builtin_fmaxf((a), (b)), (c))
; __device__ __forceinline__ void attn_unit(LAS unsigned char* lds, bf16_t* Qm, const bf16_t* __restrict__ Kb, const bf16_t* __restrict__ Vt,
;                                           int b, int h, int qb, int lgS, float lam, float oscale, const float* __restrict__ subg, float* stash) {
;     ...
;             float mx;
;             {
;                 float a_ = ATT_MX3(p0[0], p0[1], p1[0]), b_ = ATT_MX3(p0[2], p0[3], p1[1]); a_ = ATT_MX3(a_, p1[2], p1[3]);
; #pragma unroll
;                 for (int r = 4; r < 16; r += 4) { a_ = ATT_MX3(a_, p0[r], p0[r + 1]); b_ = ATT_MX3(b_, p0[r + 2], p0[r + 3]); a_ = ATT_MX3(a_, p1[r], p1[r + 1]); b_ = ATT_MX3(b_, p1[r + 2], p1[r + 3]); }
;                 const float m_ = __builtin_fmaxf(a_, b_);
;                 auto rr_ = __builtin_amdgcn_permlane32_swap(__float_as_uint(m_), __float_as_uint(m_), false, false);
;                 mx = __builtin_fmaxf(__uint_as_float(rr_[0]), __uint_as_float(rr_[1]));
;             }
;             mhat = mx;
; #pragma unroll
;             for (int r = 0; r < 16; ++r) negm[r] = -mx;
;             float sum = 0.f;
; #pragma unroll
;             for (int r = 0; r < 16; ++r) { p0[r] = __builtin_amdgcn_exp2f(p0[r] - mx); p1[r] = __builtin_amdgcn_exp2f(p1[r] - mx); sum += p0[r] + p1[r]; }
;             lrun = sum;
; #pragma unroll
;             for (int j = 0; j < 8; ++j) { pk[j >> 2][j & 3] = cvtpk_s(p0[2 * j], p0[2 * j + 1]); pk[2 + (j >> 2)][j & 3] = cvtpk_s(p1[2 * j], p1[2 * j + 1]); }
;             ATT_KRD(KBUF, 0, 1);
; #pragma unroll
;             for (int b2 = 0; b2 < 4; ++b2) vfa[b2] = *(const LAS bf16x8*)(lds + vr + b2 * 32 * VP);
;         }
;         __syncthreads();
;         int vs0 = 0, vs1 = VBUF, vs2 = 2 * VBUF;
;         int kq0 = 0, kq1 = KBUF, kq2 = 2 * KBUF;
	s_waitcnt vmcnt(1)
	v_mfma_f32_32x32x16_bf16 v[2:17], v[34:37], v[148:151], v[2:17]
	v_mfma_f32_32x32x16_bf16 v[18:33], v[38:41], v[148:151], v[18:33]
	s_nop 10
	v_max_f32_e32 v1, v3, v3
	v_max_f32_e32 v34, v2, v2
	v_max_f32_e32 v1, v34, v1
	v_max3_f32 v35, v4, v5, v19
	v_max3_f32 v1, v1, v18, v20
	v_max3_f32 v34, v35, v8, v9
	v_max3_f32 v1, v1, v21, v6
	v_max3_f32 v34, v34, v24, v25
	v_max3_f32 v1, v1, v7, v22
	v_max3_f32 v34, v34, v12, v13
	v_max3_f32 v1, v1, v23, v10
	v_max3_f32 v34, v34, v28, v29
	v_max3_f32 v1, v1, v11, v26
	v_max3_f32 v34, v34, v16, v17
	v_max3_f32 v1, v1, v27, v14
	v_max3_f32 v34, v34, v32, v33
	v_max3_f32 v1, v1, v15, v30
	v_max3_f32 v1, v1, v31, v34
	v_mov_b32_e32 v34, v1
	s_nop 1
	v_permlane32_swap_b32_e32 v1, v34
	v_max_f32_e32 v34, v34, v34
	v_max_f32_e32 v1, v1, v1
	v_max_f32_e32 v250, v1, v34
	v_sub_f32_e32 v1, v26, v250
	v_sub_f32_e32 v26, v27, v250
	v_sub_f32_e32 v27, v28, v250
	v_sub_f32_e32 v28, v29, v250
	v_sub_f32_e32 v29, v30, v250
	v_sub_f32_e32 v30, v31, v250
	v_sub_f32_e32 v31, v32, v250
	v_sub_f32_e32 v41, v18, v250
	v_sub_f32_e32 v42, v19, v250
	v_sub_f32_e32 v47, v2, v250
	v_sub_f32_e32 v32, v33, v250
	v_sub_f32_e32 v36, v13, v250
	v_sub_f32_e32 v48, v3, v250
	v_sub_f32_e32 v49, v4, v250
	v_exp_f32_e32 v3, v1
	v_exp_f32_e32 v4, v28
	v_exp_f32_e32 v13, v31
	v_exp_f32_e32 v1, v41
	v_exp_f32_e32 v28, v42
	v_exp_f32_e32 v31, v47
	v_sub_f32_e32 v33, v10, v250
	v_sub_f32_e32 v35, v12, v250
	v_sub_f32_e32 v43, v20, v250
	v_exp_f32_e32 v12, v32
	v_exp_f32_e32 v32, v48
	v_sub_f32_e32 v34, v11, v250
	v_sub_f32_e32 v38, v15, v250
	v_sub_f32_e32 v44, v21, v250
	v_sub_f32_e32 v50, v5, v250
	v_exp_f32_e32 v11, v29
	v_exp_f32_e32 v15, v33
	v_exp_f32_e32 v29, v43
	v_exp_f32_e32 v33, v49
	v_sub_f32_e32 v37, v14, v250
	v_sub_f32_e32 v22, v22, v250
	v_sub_f32_e32 v45, v23, v250
	v_exp_f32_e32 v10, v30
	v_exp_f32_e32 v14, v34
	v_exp_f32_e32 v30, v44
	v_exp_f32_e32 v34, v50
	v_sub_f32_e32 v6, v6, v250
	v_exp_f32_e32 v5, v27
	v_exp_f32_e32 v23, v22
	v_exp_f32_e32 v22, v45
	v_cvt_pk_bf16_f32 v172, v1, v28
	v_exp_f32_e32 v27, v6
	v_sub_f32_e32 v6, v7, v250
	v_add_f32_e32 v1, v1, v31
	v_exp_f32_e32 v2, v26
	v_exp_f32_e32 v26, v6
	v_sub_f32_e32 v6, v8, v250
	v_add_f32_e32 v1, 0, v1
	v_add_f32_e32 v8, v28, v32
	v_add_f32_e32 v1, v8, v1
	v_add_f32_e32 v8, v29, v33
	v_sub_f32_e32 v24, v24, v250
	v_sub_f32_e32 v46, v25, v250
	v_add_f32_e32 v1, v8, v1
	v_add_f32_e32 v8, v30, v34
	v_exp_f32_e32 v25, v24
	v_exp_f32_e32 v24, v46
	v_exp_f32_e32 v7, v6
	v_sub_f32_e32 v6, v9, v250
	v_add_f32_e32 v1, v8, v1
	v_pk_mov_b32 v[8:9], v[22:23], v[22:23] op_sel:[1,0]
	v_exp_f32_e32 v6, v6
	v_cvt_pk_bf16_f32 v174, v8, v9
	v_pk_mov_b32 v[8:9], v[26:27], v[26:27] op_sel:[1,0]
	v_sub_f32_e32 v39, v16, v250
	v_cvt_pk_bf16_f32 v202, v8, v9
	v_pk_add_f32 v[8:9], v[22:23], v[26:27]
	v_sub_f32_e32 v40, v17, v250
	v_add_f32_e32 v1, v9, v1
	v_add_f32_e32 v1, v8, v1
	v_pk_mov_b32 v[8:9], v[24:25], v[24:25] op_sel:[1,0]
	v_exp_f32_e32 v17, v35
	v_cvt_pk_bf16_f32 v175, v8, v9
	v_pk_mov_b32 v[8:9], v[6:7], v[6:7] op_sel:[1,0]
	v_pk_add_f32 v[6:7], v[24:25], v[6:7]
	v_exp_f32_e32 v16, v36
	v_add_f32_e32 v1, v7, v1
	v_add_f32_e32 v1, v6, v1
	v_pk_mov_b32 v[6:7], v[2:3], v[2:3] op_sel:[1,0]
	v_pk_add_f32 v[2:3], v[2:3], v[14:15]
	v_exp_f32_e32 v19, v37
	v_add_f32_e32 v1, v3, v1
	v_add_f32_e32 v1, v2, v1
	v_pk_mov_b32 v[2:3], v[4:5], v[4:5] op_sel:[1,0]
	v_exp_f32_e32 v18, v38
	v_cvt_pk_bf16_f32 v165, v2, v3
	v_pk_mov_b32 v[2:3], v[16:17], v[16:17] op_sel:[1,0]
	v_exp_f32_e32 v21, v39
	v_cvt_pk_bf16_f32 v181, v2, v3
	v_pk_add_f32 v[2:3], v[4:5], v[16:17]
	v_exp_f32_e32 v20, v40
	v_add_f32_e32 v1, v3, v1
	v_add_f32_e32 v1, v2, v1
	v_pk_mov_b32 v[2:3], v[10:11], v[10:11] op_sel:[1,0]
	v_xor_b32_e32 v64, 0x80000000, v250
	v_cvt_pk_bf16_f32 v166, v2, v3
	v_pk_mov_b32 v[2:3], v[18:19], v[18:19] op_sel:[1,0]
	v_cvt_pk_bf16_f32 v164, v6, v7
	v_cvt_pk_bf16_f32 v182, v2, v3
	v_pk_add_f32 v[2:3], v[10:11], v[18:19]
	v_pk_mov_b32 v[6:7], v[14:15], v[14:15] op_sel:[1,0]
	v_add_f32_e32 v1, v3, v1
	v_add_f32_e32 v1, v2, v1
	v_pk_mov_b32 v[2:3], v[12:13], v[12:13] op_sel:[1,0]
	v_cvt_pk_bf16_f32 v173, v29, v30
	v_cvt_pk_bf16_f32 v167, v2, v3
	v_pk_mov_b32 v[2:3], v[20:21], v[20:21] op_sel:[1,0]
	v_cvt_pk_bf16_f32 v200, v31, v32
	v_cvt_pk_bf16_f32 v183, v2, v3
	v_pk_add_f32 v[2:3], v[12:13], v[20:21]
	v_cvt_pk_bf16_f32 v201, v33, v34
	v_add_f32_e32 v1, v3, v1
	v_cvt_pk_bf16_f32 v203, v8, v9
	v_cvt_pk_bf16_f32 v180, v6, v7
	v_add_f32_e32 v249, v2, v1
	v_mov_b32_e32 v1, v0
	v_mov_b32_e32 v2, v0
	v_mov_b32_e32 v3, v0
	v_mov_b32_e32 v4, v0
	v_mov_b32_e32 v5, v0
	v_mov_b32_e32 v6, v0
	v_mov_b32_e32 v7, v0
	v_mov_b32_e32 v8, v0
	v_mov_b32_e32 v9, v0
	v_mov_b32_e32 v10, v0
	v_mov_b32_e32 v11, v0
	v_mov_b32_e32 v12, v0
	v_mov_b32_e32 v13, v0
	v_mov_b32_e32 v14, v0
	v_mov_b32_e32 v15, v0
	v_mov_b32_e32 v48, v0
	v_mov_b32_e32 v49, v0
	v_mov_b32_e32 v50, v0
	v_mov_b32_e32 v32, v0
	v_mov_b32_e32 v33, v0
	v_mov_b32_e32 v34, v0
	v_mov_b32_e32 v35, v0
	v_mov_b32_e32 v36, v0
	v_mov_b32_e32 v37, v0
	v_mov_b32_e32 v38, v0
	v_mov_b32_e32 v39, v0
	v_mov_b32_e32 v40, v0
	v_mov_b32_e32 v41, v0
	v_mov_b32_e32 v42, v0
	v_mov_b32_e32 v43, v0
	v_mov_b32_e32 v44, v0
	v_mov_b32_e32 v45, v0
	v_mov_b32_e32 v46, v0
	v_mov_b32_e32 v47, v0
	v_mov_b32_e32 v16, v0
	v_mov_b32_e32 v17, v0
	v_mov_b32_e32 v18, v0
	v_mov_b32_e32 v19, v0
	v_mov_b32_e32 v20, v0
	v_mov_b32_e32 v21, v0
	v_mov_b32_e32 v22, v0
	v_mov_b32_e32 v23, v0
	v_mov_b32_e32 v24, v0
	v_mov_b32_e32 v25, v0
	v_mov_b32_e32 v26, v0
	v_mov_b32_e32 v27, v0
	v_mov_b32_e32 v28, v0
	v_mov_b32_e32 v29, v0
	v_mov_b32_e32 v30, v0
	v_mov_b32_e32 v31, v0
	v_mov_b32_e32 v65, v64
	v_mov_b32_e32 v66, v64
	v_mov_b32_e32 v67, v64
	v_mov_b32_e32 v68, v64
	v_mov_b32_e32 v69, v64
	v_mov_b32_e32 v70, v64
	v_mov_b32_e32 v71, v64
	v_mov_b32_e32 v72, v64
	v_mov_b32_e32 v73, v64
	v_mov_b32_e32 v74, v64
	v_mov_b32_e32 v75, v64
	v_mov_b32_e32 v76, v64
	v_mov_b32_e32 v77, v64
	v_mov_b32_e32 v78, v64
	v_mov_b32_e32 v79, v64
	s_cmp_eq_u32 s98, 0
	s_cbranch_scc1 .Lmy_noprio
	s_setprio 1
.Lmy_noprio:
	s_mov_b32 s61, s50
	s_mov_b32 s50, s29
	s_mov_b32 s65, s28
.LBB0_335:
	v_mfma_f32_32x32x16_bf16 v[96:111], v[156:159], v[136:139], v[64:79]
	v_mfma_f32_32x32x16_bf16 v[80:95], v[160:163], v[136:139], v[64:79]
	s_add_i32 s29, s57, 3
	s_cmp_lt_u32 s29, s38
	s_cselect_b64 s[30:31], -1, 0
	s_cmp_ge_u32 s29, s38
	s_cbranch_scc1 .Lmy_skip_kw
	v_add_u32_e32 v156, s60, v248
	s_waitcnt vmcnt(0)
	ds_write_b128 v156, v[152:155]

; #define LAS __attribute__((address_space(3)))
; #define ATT_KRD(KOFF, DLO, DHI) do { _Pragma("unroll") for (int d0 = (DLO); d0 < (DHI); ++d0) { kf[2 * d0] = *(const LAS bf16x8*)(lds + (KOFF) + kr + 2 * d0 * KCH); kf[2 * d0 + 1] = *(const LAS bf16x8*)(lds + (KOFF) + kr + 2 * d0 * KCH + 512); } } while (0)
; #define ATT_SB() __builtin_amdgcn_sched_barrier(0)
; #define ATT_EXP2(J) do { float e0_, e1_; if ((J) < 8) { e0_ = __builtin_amdgcn_exp2f(p0[2 * (J)]); e1_ = __builtin_amdgcn_exp2f(p0[2 * (J) + 1]); } else { e0_ = __builtin_amdgcn_exp2f(p1[2 * (J) - 16]); e1_ = __builtin_amdgcn_exp2f(p1[2 * (J) - 15]); } \
;                 sum += e0_; sum += e1_; asm volatile("" : "+v"(sum)); pkn[(J) >> 2][(J) & 3] = cvtpk_s(e0_, e1_); } while (0)
; __device__ __forceinline__ void attn_unit(LAS unsigned char* lds, bf16_t* Qm, const bf16_t* __restrict__ Kb, const bf16_t* __restrict__ Vt,
;                                           int b, int h, int qb, int lgS, float lam, float oscale, const float* __restrict__ subg, float* stash) {
;     ...
;             for (int ks = 1; ks < 4; ++ks) {
; #pragma unroll
;                 for (int blk = 0; blk < 4; ++blk) {
;                     const int gi = (ks - 1) * 4 + blk;
;                     if (blk == 0 && ks < 3) {
; #pragma unroll
;                         for (int b2 = 0; b2 < 4; ++b2) { const bf16x8 v_ = *(const LAS bf16x8*)(lds + vs0 + vr + b2 * 32 * VP + (ks + 1) * 32); if (ks & 1) vfa[b2] = v_; else vfb[b2] = v_; }
;                     }
;                     o[blk] = __builtin_amdgcn_mfma_f32_32x32x16_bf16((ks & 1) ? vfb[blk] : vfa[blk], __builtin_bit_cast(bf16x8, pk[ks]), o[blk], 0, 0, 0);
;                     ATT_EXP2(gi);
;                     if (gi < 4) ATT_EXP2(12 + gi);
;                     ATT_SB();
;                 }
;             }
;     ...
;             lrun += sum;
; #pragma unroll
;             for (int j = 0; j < 4; ++j) pk[j] = pkn[j];
;             if (t + 2 < NT) ATT_KRD(kq2, 0, 1);
; #pragma unroll
;             for (int b2 = 0; b2 < 4; ++b2) vfa[b2] = *(const LAS bf16x8*)(lds + vs1 + vr + b2 * 32 * VP);
;             ATT_SB();
;             { const int tmp = vs0; vs0 = vs1; vs1 = vs2; vs2 = tmp; }
;             { const int tmp = kq0; kq0 = kq1; kq1 = kq2; kq2 = tmp; }
;             __syncthreads();
;         }
.Lmy_skip_m:
	s_waitcnt lgkmcnt(6)
	v_mfma_f32_32x32x16_bf16 v[32:47], v[188:191], v[172:175], v[32:47]
	ds_read_b128 v[196:199], v251 offset:25344
	v_exp_f32_e32 v108, v108
	v_exp_f32_e32 v109, v109
	v_add_f32_e32 v156, v108, v156
	v_add_f32_e32 v156, v109, v156
	s_waitcnt lgkmcnt(6)
	v_mfma_f32_32x32x16_bf16 v[16:31], v[184:187], v[172:175], v[16:31]
	ds_read_b128 v[188:191], v251 offset:34560
	ds_read_b128 v[212:215], v160 offset:4224
	ds_read_b128 v[216:219], v160 offset:4736
	v_exp_f32_e32 v110, v110
	v_exp_f32_e32 v111, v111
	v_add_f32_e32 v156, v110, v156
	v_add_f32_e32 v156, v111, v156
	s_waitcnt lgkmcnt(8)
	v_mfma_f32_32x32x16_bf16 v[0:15], v[180:183], v[164:167], v[0:15]
	ds_read_b128 v[184:187], v251 offset:39168
	ds_read_b128 v[222:225], v160 offset:6336
	ds_read_b128 v[240:243], v160 offset:6848
	v_exp_f32_e32 v80, v80
	v_exp_f32_e32 v81, v81
	v_add_f32_e32 v156, v80, v156
	v_add_f32_e32 v156, v81, v156
	v_cvt_pk_bf16_f32 v180, v104, v105
	v_cvt_pk_bf16_f32 v181, v106, v107
	v_cvt_pk_bf16_f32 v182, v108, v109
	v_cvt_pk_bf16_f32 v183, v110, v111
	s_waitcnt lgkmcnt(10)
	v_mfma_f32_32x32x16_bf16 v[48:63], v[200:203], v[164:167], v[48:63]
	v_exp_f32_e32 v82, v82
	v_exp_f32_e32 v83, v83
	v_add_f32_e32 v156, v82, v156
	v_add_f32_e32 v156, v83, v156
	v_cvt_pk_bf16_f32 v200, v96, v97
	v_cvt_pk_bf16_f32 v201, v98, v99
	v_cvt_pk_bf16_f32 v202, v100, v101
	v_cvt_pk_bf16_f32 v203, v102, v103
	v_cvt_pk_bf16_f32 v172, v80, v81
	s_waitcnt lgkmcnt(9)
	v_mfma_f32_32x32x16_bf16 v[32:47], v[204:207], v[164:167], v[32:47]
	ds_read_b128 v[204:207], v160 offset:2112
	v_exp_f32_e32 v84, v84
	v_exp_f32_e32 v85, v85
	v_add_f32_e32 v156, v84, v156
	v_add_f32_e32 v156, v85, v156
	v_cvt_pk_bf16_f32 v173, v82, v83
	s_waitcnt lgkmcnt(9)
	v_mfma_f32_32x32x16_bf16 v[16:31], v[208:211], v[164:167], v[16:31]
	ds_read_b128 v[208:211], v160 offset:2624
	v_exp_f32_e32 v86, v86
	v_exp_f32_e32 v87, v87
	v_add_f32_e32 v156, v86, v156
	v_add_f32_e32 v156, v87, v156
	v_add_f32_e32 v249, v249, v156
	ds_read_b128 v[156:159], v160
	ds_read_b128 v[160:163], v160 offset:512
	v_cvt_pk_bf16_f32 v174, v84, v85
	v_cvt_pk_bf16_f32 v175, v86, v87
	v_cvt_pk_bf16_f32 v164, v88, v89
	v_cvt_pk_bf16_f32 v165, v90, v91
	v_cvt_pk_bf16_f32 v166, v92, v93
	v_cvt_pk_bf16_f32 v167, v94, v95
	s_add_i32 s57, s57, 1
	s_add_i32 s90, s90, 64
	s_mov_b64 s[28:29], 0x10000
	v_lshl_add_u64 v[238:239], v[238:239], 0, s[28:29]
	s_mov_b32 s28, s25
	s_mov_b32 s25, s56
	s_mov_b32 s29, s60
	s_mov_b32 s60, s61
	s_mov_b32 s56, s65
	s_mov_b32 s61, s50
	s_mov_b32 s50, s29
	s_mov_b32 s65, s28
	s_waitcnt lgkmcnt(0)
	s_cmp_lg_u32 s98, 0
	s_cbranch_scc1 .Lmy_skip_e
	s_barrier
.Lmy_skip_e:
	s_cmp_eq_u32 s63, s57
	s_cbranch_scc0 .LBB0_335
	s_branch .LBB0_349

; #define LAS __attribute__((address_space(3)))
; #define GAS __attribute__((address_space(1)))
; __device__ __forceinline__ void attn_unit(LAS unsigned char* lds, bf16_t* Qm, const bf16_t* __restrict__ Kb, const bf16_t* __restrict__ Vt,
;                                           int b, int h, int qb, int lgS, float lam, float oscale, const float* __restrict__ subg, float* stash) {
;     ...
;         {
; #pragma unroll
;             for (int blk = 0; blk < 4; ++blk) o[blk] = __builtin_amdgcn_mfma_f32_32x32x16_bf16(vfa[blk], __builtin_bit_cast(bf16x8, pk[0]), o[blk], 0, 0, 0);
; #pragma unroll
;             for (int ks = 1; ks < 4; ++ks)
; #pragma unroll
;                 for (int blk = 0; blk < 4; ++blk) {
;                     const bf16x8 vf = *(const LAS bf16x8*)(lds + vs0 + vr + blk * 32 * VP + ks * 32);
;                     o[blk] = __builtin_amdgcn_mfma_f32_32x32x16_bf16(vf, __builtin_bit_cast(bf16x8, pk[ks]), o[blk], 0, 0, 0);
;                 }
;         }
;         __syncthreads();
;         lrun += __shfl_xor(lrun, 32);
;         inv = 1.0f / lrun;
;         if (c == 0) {
;             int tq_ = threadIdx.x; asm volatile("" : "+v"(tq_)); float* st_ = stash + tq_ * 64;
; #pragma unroll
;             for (int i = 0; i < 4; ++i)
; #pragma unroll
;                 for (int r = 0; r < 16; r += 4) *(GAS f32x4*)(st_ + i * 16 + r) = (f32x4){o[i][r] * inv, o[i][r + 1] * inv, o[i][r + 2] * inv, o[i][r + 3] * inv};
;         }
.Lmy_skip_pf:
	v_add_u32_e32 v72, s28, v220
	ds_read_b128 v[80:83], v72 offset:25376
	ds_read_b128 v[84:87], v72 offset:29984
	ds_read_b128 v[88:91], v72 offset:34592
	ds_read_b128 v[92:95], v72 offset:39200
	ds_read_b128 v[96:99], v72 offset:25408
	ds_read_b128 v[100:103], v72 offset:30016
	ds_read_b128 v[104:107], v72 offset:34624
	ds_read_b128 v[108:111], v72 offset:39232
	ds_read_b128 v[204:207], v72 offset:25440
	ds_read_b128 v[208:211], v72 offset:30048
	ds_read_b128 v[212:215], v72 offset:34656
	ds_read_b128 v[216:219], v72 offset:39264
	v_mfma_f32_32x32x16_bf16 v[0:15], v[196:199], v[200:203], v[0:15]
	v_mfma_f32_32x32x16_bf16 v[48:63], v[192:195], v[200:203], v[48:63]
	v_mfma_f32_32x32x16_bf16 v[32:47], v[188:191], v[200:203], v[32:47]
	v_mfma_f32_32x32x16_bf16 v[16:31], v[184:187], v[200:203], v[16:31]
	s_waitcnt lgkmcnt(8)
	v_mfma_f32_32x32x16_bf16 v[0:15], v[80:83], v[180:183], v[0:15]
	v_mfma_f32_32x32x16_bf16 v[48:63], v[84:87], v[180:183], v[48:63]
	v_mfma_f32_32x32x16_bf16 v[32:47], v[88:91], v[180:183], v[32:47]
	v_mfma_f32_32x32x16_bf16 v[16:31], v[92:95], v[180:183], v[16:31]
	s_waitcnt lgkmcnt(4)
	v_mfma_f32_32x32x16_bf16 v[0:15], v[96:99], v[172:175], v[0:15]
	v_mfma_f32_32x32x16_bf16 v[48:63], v[100:103], v[172:175], v[48:63]
	v_mfma_f32_32x32x16_bf16 v[32:47], v[104:107], v[172:175], v[32:47]
	v_mfma_f32_32x32x16_bf16 v[16:31], v[108:111], v[172:175], v[16:31]
	s_waitcnt lgkmcnt(0)
	s_barrier
	v_mfma_f32_32x32x16_bf16 v[0:15], v[204:207], v[164:167], v[0:15]
	v_mfma_f32_32x32x16_bf16 v[48:63], v[208:211], v[164:167], v[48:63]
	v_mfma_f32_32x32x16_bf16 v[32:47], v[212:215], v[164:167], v[32:47]
	v_mfma_f32_32x32x16_bf16 v[16:31], v[216:219], v[164:167], v[16:31]
	ds_bpermute_b32 v64, v246, v249
	s_waitcnt lgkmcnt(0)
	v_add_f32_e32 v64, v249, v64
	v_div_scale_f32 v65, s[28:29], v64, v64, 1.0
	v_rcp_f32_e32 v66, v65
	s_mov_b64 s[28:29], -1
	v_fma_f32 v67, -v65, v66, 1.0
	v_fmac_f32_e32 v66, v67, v66
	v_div_scale_f32 v67, vcc, 1.0, v64, 1.0
	v_mul_f32_e32 v68, v67, v66
	v_fma_f32 v69, -v65, v68, v67
	v_fmac_f32_e32 v68, v69, v66
	v_fma_f32 v65, -v65, v68, v67
	v_div_fmas_f32 v65, v65, v66, v68
	v_div_fixup_f32 v64, v65, v64, 1.0
	s_and_b64 vcc, exec, s[26:27]
	s_cbranch_vccz .LBB0_333
	v_mov_b32_e32 v65, v254
	s_mov_b64 s[28:29], 0
	v_lshlrev_b32_e32 v70, 4, v65
	v_pk_mul_f32 v[66:67], v[0:1], v[64:65] op_sel_hi:[1,0]
	v_pk_mul_f32 v[68:69], v[2:3], v[64:65] op_sel_hi:[1,0]
	global_store_dwordx4 v70, v[66:69], s[66:67]
	s_nop 1
	v_pk_mul_f32 v[66:67], v[4:5], v[64:65] op_sel_hi:[1,0]
	v_pk_mul_f32 v[68:69], v[6:7], v[64:65] op_sel_hi:[1,0]
	s_add_u32 s100, s66, 0x2000
	s_addc_u32 s101, s67, 0
	global_store_dwordx4 v70, v[66:69], s[100:101]
	s_nop 1
	v_pk_mul_f32 v[66:67], v[8:9], v[64:65] op_sel_hi:[1,0]
	v_pk_mul_f32 v[68:69], v[10:11], v[64:65] op_sel_hi:[1,0]
	s_add_u32 s100, s66, 0x4000
	s_addc_u32 s101, s67, 0
	global_store_dwordx4 v70, v[66:69], s[100:101]
	s_nop 1
	v_pk_mul_f32 v[66:67], v[12:13], v[64:65] op_sel_hi:[1,0]
	v_pk_mul_f32 v[68:69], v[14:15], v[64:65] op_sel_hi:[1,0]
	s_add_u32 s100, s66, 0x6000
	s_addc_u32 s101, s67, 0
	global_store_dwordx4 v70, v[66:69], s[100:101]
	s_nop 1
	v_pk_mul_f32 v[66:67], v[48:49], v[64:65] op_sel_hi:[1,0]
	v_pk_mul_f32 v[68:69], v[50:51], v[64:65] op_sel_hi:[1,0]
	s_add_u32 s100, s66, 0x8000
	s_addc_u32 s101, s67, 0
	global_store_dwordx4 v70, v[66:69], s[100:101]
	s_nop 1
	v_pk_mul_f32 v[66:67], v[52:53], v[64:65] op_sel_hi:[1,0]
	v_pk_mul_f32 v[68:69], v[54:55], v[64:65] op_sel_hi:[1,0]
	s_add_u32 s100, s66, 0xa000
	s_addc_u32 s101, s67, 0
	global_store_dwordx4 v70, v[66:69], s[100:101]
	s_nop 1
	v_pk_mul_f32 v[66:67], v[56:57], v[64:65] op_sel_hi:[1,0]
	v_pk_mul_f32 v[68:69], v[58:59], v[64:65] op_sel_hi:[1,0]
	s_add_u32 s100, s66, 0xc000
	s_addc_u32 s101, s67, 0
	global_store_dwordx4 v70, v[66:69], s[100:101]
	s_nop 1
	v_pk_mul_f32 v[66:67], v[60:61], v[64:65] op_sel_hi:[1,0]
	v_pk_mul_f32 v[68:69], v[62:63], v[64:65] op_sel_hi:[1,0]
	s_add_u32 s100, s66, 0xe000
	s_addc_u32 s101, s67, 0
	global_store_dwordx4 v70, v[66:69], s[100:101]
	s_nop 1
	v_pk_mul_f32 v[66:67], v[32:33], v[64:65] op_sel_hi:[1,0]
	v_pk_mul_f32 v[68:69], v[34:35], v[64:65] op_sel_hi:[1,0]
	s_add_u32 s100, s66, 0x10000
	s_addc_u32 s101, s67, 0
	global_store_dwordx4 v70, v[66:69], s[100:101]
	s_nop 1
	v_pk_mul_f32 v[66:67], v[36:37], v[64:65] op_sel_hi:[1,0]
	v_pk_mul_f32 v[68:69], v[38:39], v[64:65] op_sel_hi:[1,0]
	s_add_u32 s100, s66, 0x12000
	s_addc_u32 s101, s67, 0
	global_store_dwordx4 v70, v[66:69], s[100:101]
	s_nop 1
	v_pk_mul_f32 v[66:67], v[40:41], v[64:65] op_sel_hi:[1,0]
	v_pk_mul_f32 v[68:69], v[42:43], v[64:65] op_sel_hi:[1,0]
	s_add_u32 s100, s66, 0x14000
	s_addc_u32 s101, s67, 0
	global_store_dwordx4 v70, v[66:69], s[100:101]
	s_nop 1
	v_pk_mul_f32 v[66:67], v[44:45], v[64:65] op_sel_hi:[1,0]
	v_pk_mul_f32 v[68:69], v[46:47], v[64:65] op_sel_hi:[1,0]
	s_add_u32 s100, s66, 0x16000
	s_addc_u32 s101, s67, 0
	global_store_dwordx4 v70, v[66:69], s[100:101]
	s_nop 1
	v_pk_mul_f32 v[66:67], v[16:17], v[64:65] op_sel_hi:[1,0]
	v_pk_mul_f32 v[68:69], v[18:19], v[64:65] op_sel_hi:[1,0]
	s_add_u32 s100, s66, 0x18000
	s_addc_u32 s101, s67, 0
	global_store_dwordx4 v70, v[66:69], s[100:101]
	s_nop 1
	v_pk_mul_f32 v[66:67], v[20:21], v[64:65] op_sel_hi:[1,0]
	v_pk_mul_f32 v[68:69], v[22:23], v[64:65] op_sel_hi:[1,0]
	s_add_u32 s100, s66, 0x1a000
	s_addc_u32 s101, s67, 0
	global_store_dwordx4 v70, v[66:69], s[100:101]
	s_nop 1
	v_pk_mul_f32 v[66:67], v[24:25], v[64:65] op_sel_hi:[1,0]
	v_pk_mul_f32 v[68:69], v[26:27], v[64:65] op_sel_hi:[1,0]
	s_add_u32 s100, s66, 0x1c000
	s_addc_u32 s101, s67, 0
	global_store_dwordx4 v70, v[66:69], s[100:101]
	s_nop 1
	v_pk_mul_f32 v[66:67], v[28:29], v[64:65] op_sel_hi:[1,0]
	v_pk_mul_f32 v[68:69], v[30:31], v[64:65] op_sel_hi:[1,0]
	s_add_u32 s100, s66, 0x1e000
	s_addc_u32 s101, s67, 0
	global_store_dwordx4 v70, v[66:69], s[100:101]
	s_branch .LBB0_333
